# NP2: K-loop vmcnt(8) and lgkmcnt(0) waits folded into one s_waitcnt per segment, on top of v082
# speedup vs baseline: 1.0053x; 1.0053x over previous
.LBB0_169:
	s_add_i32 s0, s34, 2
	s_add_u32 s1, s80, 0x80
	s_addc_u32 s35, s81, 0
	s_add_i32 s47, 0, 0x10000
	s_cmp_eq_u32 s68, s34
	s_cselect_b32 s35, s43, s35
	s_cselect_b32 s34, s42, s1
	s_cselect_b32 s67, s87, vcc_hi
	s_cselect_b32 s66, s86, vcc_lo
	s_add_i32 s1, 0, 0x14000
	s_waitcnt lgkmcnt(0)
	ds_read_b128 v[130:133], v206
	ds_read_b128 v[134:137], v206 offset:1024
	ds_read_b128 v[138:141], v206 offset:2048
	ds_read_b128 v[142:145], v206 offset:3072
	ds_read_b128 v[146:149], v207
	ds_read_b128 v[150:153], v207 offset:1024
	ds_read_b128 v[154:157], v207 offset:2048
	ds_read_b128 v[158:161], v207 offset:3072
	s_add_i32 m0, s90, 0xc000
	ds_read_b128 v[162:165], v238
	ds_read_b128 v[166:169], v238 offset:1024
	ds_read_b128 v[170:173], v238 offset:2048
	ds_read_b128 v[174:177], v238 offset:3072
	ds_read_b128 v[178:181], v238 offset:4096
	ds_read_b128 v[182:185], v238 offset:5120
	ds_read_b128 v[198:201], v238 offset:6144
	ds_read_b128 v[202:205], v238 offset:7168
	global_load_lds_dwordx4 v194, s[80:81]
	s_add_i32 m0, s90, 0xe000
	s_nop 0
	global_load_lds_dwordx4 v196, s[80:81]
	s_waitcnt vmcnt(8) lgkmcnt(0)
	s_barrier
	v_mfma_f32_16x16x32_bf16 v[126:129], v[130:133], v[162:165], v[126:129]
	v_mfma_f32_16x16x32_bf16 v[122:125], v[138:141], v[162:165], v[122:125]
	v_mfma_f32_16x16x32_bf16 v[118:121], v[130:133], v[170:173], v[118:121]
	v_mfma_f32_16x16x32_bf16 v[102:105], v[138:141], v[170:173], v[102:105]
	v_mfma_f32_16x16x32_bf16 v[94:97], v[130:133], v[178:181], v[94:97]
	v_mfma_f32_16x16x32_bf16 v[90:93], v[138:141], v[178:181], v[90:93]
	v_mfma_f32_16x16x32_bf16 v[78:81], v[130:133], v[198:201], v[78:81]
	v_mfma_f32_16x16x32_bf16 v[74:77], v[138:141], v[198:201], v[74:77]
	v_mfma_f32_16x16x32_bf16 v[126:129], v[134:137], v[166:169], v[126:129]
	v_mfma_f32_16x16x32_bf16 v[122:125], v[142:145], v[166:169], v[122:125]
	v_mfma_f32_16x16x32_bf16 v[118:121], v[134:137], v[174:177], v[118:121]
	v_mfma_f32_16x16x32_bf16 v[102:105], v[142:145], v[174:177], v[102:105]
	v_mfma_f32_16x16x32_bf16 v[94:97], v[134:137], v[182:185], v[94:97]
	v_mfma_f32_16x16x32_bf16 v[90:93], v[142:145], v[182:185], v[90:93]
	v_mfma_f32_16x16x32_bf16 v[78:81], v[134:137], v[202:205], v[78:81]
	v_mfma_f32_16x16x32_bf16 v[74:77], v[142:145], v[202:205], v[74:77]
	v_mfma_f32_16x16x32_bf16 v[114:117], v[146:149], v[162:165], v[114:117]
	v_mfma_f32_16x16x32_bf16 v[110:113], v[154:157], v[162:165], v[110:113]
	v_mfma_f32_16x16x32_bf16 v[106:109], v[146:149], v[170:173], v[106:109]
	v_mfma_f32_16x16x32_bf16 v[98:101], v[154:157], v[170:173], v[98:101]
	v_mfma_f32_16x16x32_bf16 v[86:89], v[146:149], v[178:181], v[86:89]
	v_mfma_f32_16x16x32_bf16 v[82:85], v[154:157], v[178:181], v[82:85]
	v_mfma_f32_16x16x32_bf16 v[70:73], v[146:149], v[198:201], v[70:73]
	v_mfma_f32_16x16x32_bf16 v[66:69], v[154:157], v[198:201], v[66:69]
	v_mfma_f32_16x16x32_bf16 v[114:117], v[150:153], v[166:169], v[114:117]
	v_mfma_f32_16x16x32_bf16 v[110:113], v[158:161], v[166:169], v[110:113]
	v_mfma_f32_16x16x32_bf16 v[106:109], v[150:153], v[174:177], v[106:109]
	v_mfma_f32_16x16x32_bf16 v[98:101], v[158:161], v[174:177], v[98:101]
	v_mfma_f32_16x16x32_bf16 v[86:89], v[150:153], v[182:185], v[86:89]
	v_mfma_f32_16x16x32_bf16 v[82:85], v[158:161], v[182:185], v[82:85]
	v_mfma_f32_16x16x32_bf16 v[70:73], v[150:153], v[202:205], v[70:73]
	v_mfma_f32_16x16x32_bf16 v[66:69], v[158:161], v[202:205], v[66:69]
	s_barrier
	s_add_i32 s47, s47, s57
	s_mov_b32 m0, s47
	ds_read_b128 v[162:165], v238 offset:16384
	ds_read_b128 v[166:169], v238 offset:17408
	ds_read_b128 v[170:173], v238 offset:18432
	ds_read_b128 v[174:177], v238 offset:19456
	ds_read_b128 v[178:181], v238 offset:20480
	ds_read_b128 v[182:185], v238 offset:21504
	ds_read_b128 v[198:201], v238 offset:22528
	ds_read_b128 v[202:205], v238 offset:23552
	global_load_lds_dwordx4 v188, s[66:67]
	s_add_i32 m0, s47, 0x2000
	s_add_u32 s100, s66, s69
	s_addc_u32 s101, s67, 0
	s_add_i32 s1, s1, s57
	global_load_lds_dwordx4 v192, s[66:67]
	s_mov_b32 m0, s1
	s_nop 0
	global_load_lds_dwordx4 v188, s[100:101]
	s_add_i32 m0, s1, 0x2000
	s_nop 0
	global_load_lds_dwordx4 v192, s[100:101]
	s_mov_b32 m0, s90
	s_nop 0
	global_load_lds_dwordx4 v186, s[34:35]
	s_mov_b32 m0, s60
	s_nop 0
	global_load_lds_dwordx4 v190, s[34:35]
	s_waitcnt vmcnt(8) lgkmcnt(0)
	s_barrier
	v_mfma_f32_16x16x32_bf16 v[62:65], v[130:133], v[162:165], v[62:65]
	v_mfma_f32_16x16x32_bf16 v[58:61], v[138:141], v[162:165], v[58:61]
	v_mfma_f32_16x16x32_bf16 v[46:49], v[130:133], v[170:173], v[46:49]
	v_mfma_f32_16x16x32_bf16 v[42:45], v[138:141], v[170:173], v[42:45]
	v_mfma_f32_16x16x32_bf16 v[30:33], v[130:133], v[178:181], v[30:33]
	v_mfma_f32_16x16x32_bf16 v[26:29], v[138:141], v[178:181], v[26:29]
	v_mfma_f32_16x16x32_bf16 v[14:17], v[130:133], v[198:201], v[14:17]
	v_mfma_f32_16x16x32_bf16 v[10:13], v[138:141], v[198:201], v[10:13]
	v_mfma_f32_16x16x32_bf16 v[62:65], v[134:137], v[166:169], v[62:65]
	v_mfma_f32_16x16x32_bf16 v[58:61], v[142:145], v[166:169], v[58:61]
	v_mfma_f32_16x16x32_bf16 v[46:49], v[134:137], v[174:177], v[46:49]
	v_mfma_f32_16x16x32_bf16 v[42:45], v[142:145], v[174:177], v[42:45]
	v_mfma_f32_16x16x32_bf16 v[30:33], v[134:137], v[182:185], v[30:33]
	v_mfma_f32_16x16x32_bf16 v[26:29], v[142:145], v[182:185], v[26:29]
	v_mfma_f32_16x16x32_bf16 v[14:17], v[134:137], v[202:205], v[14:17]
	v_mfma_f32_16x16x32_bf16 v[10:13], v[142:145], v[202:205], v[10:13]
	v_mfma_f32_16x16x32_bf16 v[54:57], v[146:149], v[162:165], v[54:57]
	v_mfma_f32_16x16x32_bf16 v[50:53], v[154:157], v[162:165], v[50:53]
	v_mfma_f32_16x16x32_bf16 v[38:41], v[146:149], v[170:173], v[38:41]
	v_mfma_f32_16x16x32_bf16 v[34:37], v[154:157], v[170:173], v[34:37]
	v_mfma_f32_16x16x32_bf16 v[22:25], v[146:149], v[178:181], v[22:25]
	v_mfma_f32_16x16x32_bf16 v[18:21], v[154:157], v[178:181], v[18:21]
	v_mfma_f32_16x16x32_bf16 v[6:9], v[146:149], v[198:201], v[6:9]
	v_mfma_f32_16x16x32_bf16 v[2:5], v[154:157], v[198:201], v[2:5]
	v_mfma_f32_16x16x32_bf16 v[54:57], v[150:153], v[166:169], v[54:57]
	v_mfma_f32_16x16x32_bf16 v[50:53], v[158:161], v[166:169], v[50:53]
	v_mfma_f32_16x16x32_bf16 v[38:41], v[150:153], v[174:177], v[38:41]
	v_mfma_f32_16x16x32_bf16 v[34:37], v[158:161], v[174:177], v[34:37]
	v_mfma_f32_16x16x32_bf16 v[22:25], v[150:153], v[182:185], v[22:25]
	v_mfma_f32_16x16x32_bf16 v[18:21], v[158:161], v[182:185], v[18:21]
	v_mfma_f32_16x16x32_bf16 v[6:9], v[150:153], v[202:205], v[6:9]
	v_mfma_f32_16x16x32_bf16 v[2:5], v[158:161], v[202:205], v[2:5]
	s_barrier
	s_add_i32 s1, 0, 0x18000
	s_add_i32 s47, 0, 0x1c000
	ds_read_b128 v[130:133], v208
	ds_read_b128 v[134:137], v208 offset:1024
	ds_read_b128 v[138:141], v208 offset:2048
	ds_read_b128 v[142:145], v208 offset:3072
	ds_read_b128 v[146:149], v209
	ds_read_b128 v[150:153], v209 offset:1024
	ds_read_b128 v[154:157], v209 offset:2048
	ds_read_b128 v[158:161], v209 offset:3072
	s_mov_b32 m0, s61
	ds_read_b128 v[162:165], v238 offset:32768
	ds_read_b128 v[166:169], v238 offset:33792
	ds_read_b128 v[170:173], v238 offset:34816
	ds_read_b128 v[174:177], v238 offset:35840
	ds_read_b128 v[178:181], v238 offset:36864
	ds_read_b128 v[182:185], v238 offset:37888
	ds_read_b128 v[198:201], v238 offset:38912
	ds_read_b128 v[202:205], v238 offset:39936
	global_load_lds_dwordx4 v194, s[34:35]
	s_mov_b32 m0, s71
	s_nop 0
	global_load_lds_dwordx4 v196, s[34:35]
	s_waitcnt vmcnt(8) lgkmcnt(0)
	s_barrier
	v_mfma_f32_16x16x32_bf16 v[126:129], v[130:133], v[162:165], v[126:129]
	v_mfma_f32_16x16x32_bf16 v[122:125], v[138:141], v[162:165], v[122:125]
	v_mfma_f32_16x16x32_bf16 v[118:121], v[130:133], v[170:173], v[118:121]
	v_mfma_f32_16x16x32_bf16 v[102:105], v[138:141], v[170:173], v[102:105]
	v_mfma_f32_16x16x32_bf16 v[94:97], v[130:133], v[178:181], v[94:97]
	v_mfma_f32_16x16x32_bf16 v[90:93], v[138:141], v[178:181], v[90:93]
	v_mfma_f32_16x16x32_bf16 v[78:81], v[130:133], v[198:201], v[78:81]
	v_mfma_f32_16x16x32_bf16 v[74:77], v[138:141], v[198:201], v[74:77]
	v_mfma_f32_16x16x32_bf16 v[126:129], v[134:137], v[166:169], v[126:129]
	v_mfma_f32_16x16x32_bf16 v[122:125], v[142:145], v[166:169], v[122:125]
	v_mfma_f32_16x16x32_bf16 v[118:121], v[134:137], v[174:177], v[118:121]
	v_mfma_f32_16x16x32_bf16 v[102:105], v[142:145], v[174:177], v[102:105]
	v_mfma_f32_16x16x32_bf16 v[94:97], v[134:137], v[182:185], v[94:97]
	v_mfma_f32_16x16x32_bf16 v[90:93], v[142:145], v[182:185], v[90:93]
	v_mfma_f32_16x16x32_bf16 v[78:81], v[134:137], v[202:205], v[78:81]
	v_mfma_f32_16x16x32_bf16 v[74:77], v[142:145], v[202:205], v[74:77]
	v_mfma_f32_16x16x32_bf16 v[114:117], v[146:149], v[162:165], v[114:117]
	v_mfma_f32_16x16x32_bf16 v[110:113], v[154:157], v[162:165], v[110:113]
	v_mfma_f32_16x16x32_bf16 v[106:109], v[146:149], v[170:173], v[106:109]
	v_mfma_f32_16x16x32_bf16 v[98:101], v[154:157], v[170:173], v[98:101]
	v_mfma_f32_16x16x32_bf16 v[86:89], v[146:149], v[178:181], v[86:89]
	v_mfma_f32_16x16x32_bf16 v[82:85], v[154:157], v[178:181], v[82:85]
	v_mfma_f32_16x16x32_bf16 v[70:73], v[146:149], v[198:201], v[70:73]
	v_mfma_f32_16x16x32_bf16 v[66:69], v[154:157], v[198:201], v[66:69]
	v_mfma_f32_16x16x32_bf16 v[114:117], v[150:153], v[166:169], v[114:117]
	v_mfma_f32_16x16x32_bf16 v[110:113], v[158:161], v[166:169], v[110:113]
	v_mfma_f32_16x16x32_bf16 v[106:109], v[150:153], v[174:177], v[106:109]
	v_mfma_f32_16x16x32_bf16 v[98:101], v[158:161], v[174:177], v[98:101]
	v_mfma_f32_16x16x32_bf16 v[86:89], v[150:153], v[182:185], v[86:89]
	v_mfma_f32_16x16x32_bf16 v[82:85], v[158:161], v[182:185], v[82:85]
	v_mfma_f32_16x16x32_bf16 v[70:73], v[150:153], v[202:205], v[70:73]
	v_mfma_f32_16x16x32_bf16 v[66:69], v[158:161], v[202:205], v[66:69]
	s_barrier
	s_add_i32 s1, s1, s57
	s_add_u32 s66, s66, 0x80
	s_addc_u32 s67, s67, 0
	s_add_u32 s100, s100, 0x80
	s_addc_u32 s101, s101, 0
	s_add_u32 s34, s34, 0x80
	s_addc_u32 s35, s35, 0
	s_mov_b32 m0, s1
	ds_read_b128 v[162:165], v238 offset:49152
	ds_read_b128 v[166:169], v238 offset:50176
	ds_read_b128 v[170:173], v238 offset:51200
	ds_read_b128 v[174:177], v238 offset:52224
	ds_read_b128 v[178:181], v238 offset:53248
	ds_read_b128 v[182:185], v238 offset:54272
	ds_read_b128 v[198:201], v238 offset:55296
	ds_read_b128 v[202:205], v238 offset:56320
	global_load_lds_dwordx4 v188, s[66:67]
	s_add_i32 m0, s1, 0x2000
	s_add_i32 s1, s47, s57
	global_load_lds_dwordx4 v192, s[66:67]
	s_mov_b32 m0, s1
	s_nop 0
	global_load_lds_dwordx4 v188, s[100:101]
	s_add_i32 m0, s1, 0x2000
	s_nop 0
	global_load_lds_dwordx4 v192, s[100:101]
	s_mov_b32 m0, s64
	s_nop 0
	global_load_lds_dwordx4 v186, s[34:35]
	s_mov_b32 m0, s65
	s_nop 0
	global_load_lds_dwordx4 v190, s[34:35]
	s_waitcnt vmcnt(8) lgkmcnt(0)
	s_barrier
	v_mfma_f32_16x16x32_bf16 v[62:65], v[130:133], v[162:165], v[62:65]
	v_mfma_f32_16x16x32_bf16 v[58:61], v[138:141], v[162:165], v[58:61]
	v_mfma_f32_16x16x32_bf16 v[46:49], v[130:133], v[170:173], v[46:49]
	v_mfma_f32_16x16x32_bf16 v[42:45], v[138:141], v[170:173], v[42:45]
	v_mfma_f32_16x16x32_bf16 v[30:33], v[130:133], v[178:181], v[30:33]
	v_mfma_f32_16x16x32_bf16 v[26:29], v[138:141], v[178:181], v[26:29]
	v_mfma_f32_16x16x32_bf16 v[14:17], v[130:133], v[198:201], v[14:17]
	v_mfma_f32_16x16x32_bf16 v[10:13], v[138:141], v[198:201], v[10:13]
	v_mfma_f32_16x16x32_bf16 v[62:65], v[134:137], v[166:169], v[62:65]
	v_mfma_f32_16x16x32_bf16 v[58:61], v[142:145], v[166:169], v[58:61]
	v_mfma_f32_16x16x32_bf16 v[46:49], v[134:137], v[174:177], v[46:49]
	v_mfma_f32_16x16x32_bf16 v[42:45], v[142:145], v[174:177], v[42:45]
	v_mfma_f32_16x16x32_bf16 v[30:33], v[134:137], v[182:185], v[30:33]
	v_mfma_f32_16x16x32_bf16 v[26:29], v[142:145], v[182:185], v[26:29]
	v_mfma_f32_16x16x32_bf16 v[14:17], v[134:137], v[202:205], v[14:17]
	v_mfma_f32_16x16x32_bf16 v[10:13], v[142:145], v[202:205], v[10:13]
	v_mfma_f32_16x16x32_bf16 v[54:57], v[146:149], v[162:165], v[54:57]
	v_mfma_f32_16x16x32_bf16 v[50:53], v[154:157], v[162:165], v[50:53]
	v_mfma_f32_16x16x32_bf16 v[38:41], v[146:149], v[170:173], v[38:41]
	v_mfma_f32_16x16x32_bf16 v[34:37], v[154:157], v[170:173], v[34:37]
	v_mfma_f32_16x16x32_bf16 v[22:25], v[146:149], v[178:181], v[22:25]
	v_mfma_f32_16x16x32_bf16 v[18:21], v[154:157], v[178:181], v[18:21]
	v_mfma_f32_16x16x32_bf16 v[6:9], v[146:149], v[198:201], v[6:9]
	v_mfma_f32_16x16x32_bf16 v[2:5], v[154:157], v[198:201], v[2:5]
	v_mfma_f32_16x16x32_bf16 v[54:57], v[150:153], v[166:169], v[54:57]
	v_mfma_f32_16x16x32_bf16 v[50:53], v[158:161], v[166:169], v[50:53]
	v_mfma_f32_16x16x32_bf16 v[38:41], v[150:153], v[174:177], v[38:41]
	v_mfma_f32_16x16x32_bf16 v[34:37], v[158:161], v[174:177], v[34:37]
	v_mfma_f32_16x16x32_bf16 v[22:25], v[150:153], v[182:185], v[22:25]
	v_mfma_f32_16x16x32_bf16 v[18:21], v[158:161], v[182:185], v[18:21]
	v_mfma_f32_16x16x32_bf16 v[6:9], v[150:153], v[202:205], v[6:9]
	v_mfma_f32_16x16x32_bf16 v[2:5], v[158:161], v[202:205], v[2:5]
	s_barrier
	s_add_u32 s80, s80, 0x100
	s_addc_u32 s81, s81, 0
	s_add_u32 vcc_lo, vcc_lo, 0x100
	s_addc_u32 vcc_hi, vcc_hi, 0
	s_cmp_ge_u32 s0, s91
	s_mov_b32 s34, s0
	s_cbranch_scc0 .LBB0_169
	v_readlane_b32 s0, v243, 28
	v_readlane_b32 s1, v243, 29
	s_and_b64 vcc, exec, s[0:1]
	s_cbranch_vccz .LBB0_174
	s_barrier
	v_lshl_add_u32 v198, s99, 8, v1
	s_cmp_lt_i32 s70, 1
	s_mov_b64 s[34:35], -1
	s_cbranch_scc0 .LBB0_175
